# P0 rotary tables: the 8 position loads per thread issued together, 8 unrolled bodies with counted waits (was: load, wait for it and for the previous stores, compute, store)
# speedup vs baseline: 1.0021x; 1.0021x over previous
.LBB0_103:
	s_or_b64 exec, exec, s[14:15]
	v_lshl_add_u32 v0, s54, 9, v56
	s_mov_b32 s0, 0x100000
	v_cmp_gt_i32_e32 vcc, s0, v0
	s_and_saveexec_b64 s[0:1], vcc
	s_cbranch_execz .LBB0_106
	s_waitcnt lgkmcnt(1)
	v_and_b32_e32 v1, 31, v56
	v_cvt_f32_ubyte0_e32 v1, v1
	v_mul_f32_e32 v2, 0xbed49a78, v1
	s_mov_b32 s6, 0xc2fc0000
	v_mov_b32_e32 v3, 0x42800000
	v_cmp_gt_f32_e32 vcc, s6, v2
	v_readlane_b32 s8, v250, 0
	s_lshl_b32 s6, s56, 9
	v_cndmask_b32_e32 v2, 0, v3, vcc
	v_fmac_f32_e32 v2, 0xbed49a78, v1
	v_exp_f32_e32 v1, v2
	v_not_b32_e32 v2, 63
	v_cndmask_b32_e32 v2, 0, v2, vcc
	v_readlane_b32 s9, v250, 1
	v_ldexp_f32 v4, v1, v2
	v_ashrrev_i32_e32 v1, 31, v0
	v_lshl_add_u64 v[2:3], v[0:1], 2, s[8:9]
	s_mov_b64 s[8:9], 0x6000000
	s_ashr_i32 s7, s6, 31
	s_mov_b32 s14, 0x6dc9c883
	v_lshl_add_u64 v[2:3], v[2:3], 0, s[8:9]
	s_lshl_b64 s[8:9], s[6:7], 2
	s_mov_b64 s[12:13], 0
	s_mov_b32 s15, 0x3fc45f30
	s_mov_b32 s7, 0xfffff
	s_cmp_eq_u32 s6, 0x20000
	s_cbranch_scc0 .Lrot_loop
	v_ashrrev_i32_e32 v6, 5, v0
	v_ashrrev_i32_e32 v7, 31, v6
	v_lshl_add_u64 v[6:7], v[6:7], 2, s[36:37]
	global_load_dword v144, v[6:7], off
	v_add_co_u32_e32 v6, vcc, 0x4000, v6
	s_nop 0
	v_addc_co_u32_e32 v7, vcc, 0, v7, vcc
	global_load_dword v145, v[6:7], off
	v_add_co_u32_e32 v6, vcc, 0x4000, v6
	s_nop 0
	v_addc_co_u32_e32 v7, vcc, 0, v7, vcc
	global_load_dword v146, v[6:7], off
	v_add_co_u32_e32 v6, vcc, 0x4000, v6
	s_nop 0
	v_addc_co_u32_e32 v7, vcc, 0, v7, vcc
	global_load_dword v147, v[6:7], off
	v_add_co_u32_e32 v6, vcc, 0x4000, v6
	s_nop 0
	v_addc_co_u32_e32 v7, vcc, 0, v7, vcc
	global_load_dword v148, v[6:7], off
	v_add_co_u32_e32 v6, vcc, 0x4000, v6
	s_nop 0
	v_addc_co_u32_e32 v7, vcc, 0, v7, vcc
	global_load_dword v149, v[6:7], off
	v_add_co_u32_e32 v6, vcc, 0x4000, v6
	s_nop 0
	v_addc_co_u32_e32 v7, vcc, 0, v7, vcc
	global_load_dword v150, v[6:7], off
	v_add_co_u32_e32 v6, vcc, 0x4000, v6
	s_nop 0
	v_addc_co_u32_e32 v7, vcc, 0, v7, vcc
	global_load_dword v151, v[6:7], off
	s_waitcnt lgkmcnt(0)
	s_waitcnt vmcnt(7)
	v_cvt_f32_i32_e32 v1, v144
	v_mul_f32_e32 v1, v4, v1
	v_cvt_f64_f32_e32 v[8:9], v1
	v_mul_f64 v[10:11], v[8:9], s[14:15]
	v_rndne_f64_e32 v[10:11], v[10:11]
	v_fma_f64 v[8:9], v[8:9], s[14:15], -v[10:11]
	v_cvt_f32_f64_e32 v1, v[8:9]
	v_add_co_u32_e32 v6, vcc, 0xffc00000, v2
	s_nop 0
	v_addc_co_u32_e32 v7, vcc, -1, v3, vcc
	v_sin_f32_e32 v5, v1
	v_cos_f32_e32 v1, v1
	s_nop 0
	global_store_dword v[2:3], v5, off
	global_store_dword v[6:7], v1, off
	v_lshl_add_u64 v[2:3], v[2:3], 0, s[8:9]
	s_waitcnt vmcnt(8)
	v_cvt_f32_i32_e32 v1, v145
	v_mul_f32_e32 v1, v4, v1
	v_cvt_f64_f32_e32 v[8:9], v1
	v_mul_f64 v[10:11], v[8:9], s[14:15]
	v_rndne_f64_e32 v[10:11], v[10:11]
	v_fma_f64 v[8:9], v[8:9], s[14:15], -v[10:11]
	v_cvt_f32_f64_e32 v1, v[8:9]
	v_add_co_u32_e32 v6, vcc, 0xffc00000, v2
	s_nop 0
	v_addc_co_u32_e32 v7, vcc, -1, v3, vcc
	v_sin_f32_e32 v5, v1
	v_cos_f32_e32 v1, v1
	s_nop 0
	global_store_dword v[2:3], v5, off
	global_store_dword v[6:7], v1, off
	v_lshl_add_u64 v[2:3], v[2:3], 0, s[8:9]
	s_waitcnt vmcnt(9)
	v_cvt_f32_i32_e32 v1, v146
	v_mul_f32_e32 v1, v4, v1
	v_cvt_f64_f32_e32 v[8:9], v1
	v_mul_f64 v[10:11], v[8:9], s[14:15]
	v_rndne_f64_e32 v[10:11], v[10:11]
	v_fma_f64 v[8:9], v[8:9], s[14:15], -v[10:11]
	v_cvt_f32_f64_e32 v1, v[8:9]
	v_add_co_u32_e32 v6, vcc, 0xffc00000, v2
	s_nop 0
	v_addc_co_u32_e32 v7, vcc, -1, v3, vcc
	v_sin_f32_e32 v5, v1
	v_cos_f32_e32 v1, v1
	s_nop 0
	global_store_dword v[2:3], v5, off
	global_store_dword v[6:7], v1, off
	v_lshl_add_u64 v[2:3], v[2:3], 0, s[8:9]
	s_waitcnt vmcnt(10)
	v_cvt_f32_i32_e32 v1, v147
	v_mul_f32_e32 v1, v4, v1
	v_cvt_f64_f32_e32 v[8:9], v1
	v_mul_f64 v[10:11], v[8:9], s[14:15]
	v_rndne_f64_e32 v[10:11], v[10:11]
	v_fma_f64 v[8:9], v[8:9], s[14:15], -v[10:11]
	v_cvt_f32_f64_e32 v1, v[8:9]
	v_add_co_u32_e32 v6, vcc, 0xffc00000, v2
	s_nop 0
	v_addc_co_u32_e32 v7, vcc, -1, v3, vcc
	v_sin_f32_e32 v5, v1
	v_cos_f32_e32 v1, v1
	s_nop 0
	global_store_dword v[2:3], v5, off
	global_store_dword v[6:7], v1, off
	v_lshl_add_u64 v[2:3], v[2:3], 0, s[8:9]
	s_waitcnt vmcnt(11)
	v_cvt_f32_i32_e32 v1, v148
	v_mul_f32_e32 v1, v4, v1
	v_cvt_f64_f32_e32 v[8:9], v1
	v_mul_f64 v[10:11], v[8:9], s[14:15]
	v_rndne_f64_e32 v[10:11], v[10:11]
	v_fma_f64 v[8:9], v[8:9], s[14:15], -v[10:11]
	v_cvt_f32_f64_e32 v1, v[8:9]
	v_add_co_u32_e32 v6, vcc, 0xffc00000, v2
	s_nop 0
	v_addc_co_u32_e32 v7, vcc, -1, v3, vcc
	v_sin_f32_e32 v5, v1
	v_cos_f32_e32 v1, v1
	s_nop 0
	global_store_dword v[2:3], v5, off
	global_store_dword v[6:7], v1, off
	v_lshl_add_u64 v[2:3], v[2:3], 0, s[8:9]
	s_waitcnt vmcnt(12)
	v_cvt_f32_i32_e32 v1, v149
	v_mul_f32_e32 v1, v4, v1
	v_cvt_f64_f32_e32 v[8:9], v1
	v_mul_f64 v[10:11], v[8:9], s[14:15]
	v_rndne_f64_e32 v[10:11], v[10:11]
	v_fma_f64 v[8:9], v[8:9], s[14:15], -v[10:11]
	v_cvt_f32_f64_e32 v1, v[8:9]
	v_add_co_u32_e32 v6, vcc, 0xffc00000, v2
	s_nop 0
	v_addc_co_u32_e32 v7, vcc, -1, v3, vcc
	v_sin_f32_e32 v5, v1
	v_cos_f32_e32 v1, v1
	s_nop 0
	global_store_dword v[2:3], v5, off
	global_store_dword v[6:7], v1, off
	v_lshl_add_u64 v[2:3], v[2:3], 0, s[8:9]
	s_waitcnt vmcnt(13)
	v_cvt_f32_i32_e32 v1, v150
	v_mul_f32_e32 v1, v4, v1
	v_cvt_f64_f32_e32 v[8:9], v1
	v_mul_f64 v[10:11], v[8:9], s[14:15]
	v_rndne_f64_e32 v[10:11], v[10:11]
	v_fma_f64 v[8:9], v[8:9], s[14:15], -v[10:11]
	v_cvt_f32_f64_e32 v1, v[8:9]
	v_add_co_u32_e32 v6, vcc, 0xffc00000, v2
	s_nop 0
	v_addc_co_u32_e32 v7, vcc, -1, v3, vcc
	v_sin_f32_e32 v5, v1
	v_cos_f32_e32 v1, v1
	s_nop 0
	global_store_dword v[2:3], v5, off
	global_store_dword v[6:7], v1, off
	v_lshl_add_u64 v[2:3], v[2:3], 0, s[8:9]
	s_waitcnt vmcnt(14)
	v_cvt_f32_i32_e32 v1, v151
	v_mul_f32_e32 v1, v4, v1
	v_cvt_f64_f32_e32 v[8:9], v1
	v_mul_f64 v[10:11], v[8:9], s[14:15]
	v_rndne_f64_e32 v[10:11], v[10:11]
	v_fma_f64 v[8:9], v[8:9], s[14:15], -v[10:11]
	v_cvt_f32_f64_e32 v1, v[8:9]
	v_add_co_u32_e32 v6, vcc, 0xffc00000, v2
	s_nop 0
	v_addc_co_u32_e32 v7, vcc, -1, v3, vcc
	v_sin_f32_e32 v5, v1
	v_cos_f32_e32 v1, v1
	s_nop 0
	global_store_dword v[2:3], v5, off
	global_store_dword v[6:7], v1, off
	v_lshl_add_u64 v[2:3], v[2:3], 0, s[8:9]
	s_branch .LBB0_106
.Lrot_loop:
.LBB0_105:
	v_ashrrev_i32_e32 v6, 5, v0
	v_ashrrev_i32_e32 v7, 31, v6
	v_lshl_add_u64 v[6:7], v[6:7], 2, s[36:37]
	global_load_dword v1, v[6:7], off
	v_add_co_u32_e32 v6, vcc, 0xffc00000, v2
	v_add_u32_e32 v0, s6, v0
	s_nop 0
	v_addc_co_u32_e32 v7, vcc, -1, v3, vcc
	v_cmp_lt_i32_e32 vcc, s7, v0
	s_or_b64 s[12:13], vcc, s[12:13]
	s_waitcnt vmcnt(0)
	v_cvt_f32_i32_e32 v1, v1
	v_mul_f32_e32 v1, v4, v1
	v_cvt_f64_f32_e32 v[8:9], v1
	v_mul_f64 v[10:11], v[8:9], s[14:15]
	v_rndne_f64_e32 v[10:11], v[10:11]
	v_fma_f64 v[8:9], v[8:9], s[14:15], -v[10:11]
	v_cvt_f32_f64_e32 v1, v[8:9]
	s_waitcnt lgkmcnt(0)
	v_sin_f32_e32 v5, v1
	v_cos_f32_e32 v1, v1
	global_store_dword v[2:3], v5, off
	global_store_dword v[6:7], v1, off
	v_lshl_add_u64 v[2:3], v[2:3], 0, s[8:9]
	s_andn2_b64 exec, exec, s[12:13]
	s_cbranch_execnz .LBB0_105
